# rwkv scans: keep-y-per-lane via one v_cndmask dpp row_shr shift register instead of v_cmp plus v_cndmask
# baseline (speedup 1.0000x reference)
; template <bool DUAL>
; __device__ __forceinline__ void rwkv_tile(const Params& p, int l, int tile, unsigned char* smem) {
;     ...
; #pragma unroll 2
;       for (int i = 0; i < 32; ++i) {
;         const int inx = (i + 1) & 31;
;         const float4 nw4 = *(const float4*)(rp + inx * 384), nkk4 = *(const float4*)(rp + inx * 384 + 64), nkb4 = *(const float4*)(rp + inx * 384 + 128);
;         const float4 nkd4 = *(const float4*)(rp + inx * 384 + 192), nr4 = *(const float4*)(rp + inx * 384 + 256);
;         const float nv = vp[inx * 384];
;         v2f t = sA * (v2f){kk4.x, kk4.y};
;         t = sB * (v2f){kk4.z, kk4.w} + t;
;         float sa = t.x + t.y, ia = 0.f;
;         if (DUAL) {
;           v2f ti = iA * (v2f){kk4.x, kk4.y};
;           ti = iB * (v2f){kk4.z, kk4.w} + ti;
;           ia = ti.x + ti.y;
;           sa += dppf<0xB1>(sa); ia += dppf<0xB1>(ia);
;           sa += dppf<0x4E>(sa); ia += dppf<0x4E>(ia);
;           sa += dppf<0x141>(sa); ia += dppf<0x141>(ia);
;           sa += dppf<0x140>(sa); ia += dppf<0x140>(ia);
;         } else {
;           sa = sum16(sa);
;         }
;         v2f cA = sA * (v2f){w4.x, w4.y} + (v2f){kd4.x, kd4.y} * v;
;         v2f cB = sB * (v2f){w4.z, w4.w} + (v2f){kd4.z, kd4.w} * v;
;         sA = cA - (v2f){kb4.x, kb4.y} * sa;
;         sB = cB - (v2f){kb4.z, kb4.w} * sa;
;         v2f u = sA * (v2f){r4.x, r4.y};
;         u = sB * (v2f){r4.z, r4.w} + u;
;         float y = u.x + u.y, g = 0.f;
;         if (DUAL) {
;           iA = iA * (v2f){w4.x, w4.y} - (v2f){kb4.x, kb4.y} * ia;
;           iB = iB * (v2f){w4.z, w4.w} - (v2f){kb4.z, kb4.w} * ia;
;           v2f ui = iA * (v2f){r4.x, r4.y};
;           ui = iB * (v2f){r4.z, r4.w} + ui;
;           g = ui.x + ui.y;
;           y += dppf<0xB1>(y); g += dppf<0xB1>(g);
;           y += dppf<0x4E>(y); g += dppf<0x4E>(g);
;           y += dppf<0x141>(y); g += dppf<0x141>(g);
;           y += dppf<0x140>(y); g += dppf<0x140>(g);
;           if (fr == (i & 15)) gkeep = g;
;         } else {
;           y = sum16(y);
;         }
;         if (fr == (i & 15)) ykeep = y;
.Lrw_du_scan:
	v_mov_b32_e32 v74, v102
	v_mov_b32_e32 v75, v103
	v_cmp_eq_u32_e32 vcc, 0, v101
	ds_read_b128 v[220:223], v74 offset:25600
	ds_read_b128 v[216:219], v74 offset:25344
	ds_read_b128 v[228:231], v74 offset:26112
	ds_read_b32 v236, v75 offset:26624
	ds_read_b128 v[224:227], v74 offset:25856
	ds_read_b128 v[232:235], v74 offset:26368
	ds_read_b128 v[126:129], v74 offset:27136
	ds_read_b128 v[122:125], v74 offset:26880
	ds_read_b128 v[134:137], v74 offset:27648
	ds_read_b32 v142, v75 offset:28160
	ds_read_b128 v[130:133], v74 offset:27392
	ds_read_b128 v[138:141], v74 offset:27904
	s_mov_b32 s55, 0
.Lrw_du_loop:
	s_waitcnt lgkmcnt(6)
	v_pk_mul_f32 v[60:61], v[94:95], v[220:221]
	v_pk_mul_f32 v[62:63], v[88:89], v[220:221]
	v_pk_fma_f32 v[60:61], v[92:93], v[222:223], v[60:61]
	v_pk_fma_f32 v[62:63], v[90:91], v[222:223], v[62:63]
	v_add_f32_e32 v64, v64, v65
	v_add_f32_e32 v66, v66, v67
	v_add_f32_e32 v60, v60, v61
	v_add_f32_e32 v62, v62, v63
	v_pk_mul_f32 v[94:95], v[94:95], v[216:217]
	v_pk_mul_f32 v[92:93], v[92:93], v[218:219]
	v_add_f32_dpp v60, v60, v60 quad_perm:[1,0,3,2] row_mask:0xf bank_mask:0xf bound_ctrl:1
	v_add_f32_dpp v62, v62, v62 quad_perm:[1,0,3,2] row_mask:0xf bank_mask:0xf bound_ctrl:1
	v_add_f32_dpp v64, v64, v64 quad_perm:[1,0,3,2] row_mask:0xf bank_mask:0xf bound_ctrl:1
	v_add_f32_dpp v66, v66, v66 quad_perm:[1,0,3,2] row_mask:0xf bank_mask:0xf bound_ctrl:1
	v_pk_fma_f32 v[94:95], v[236:237], v[228:229], v[94:95] op_sel_hi:[0,1,1]
	v_add_f32_dpp v60, v60, v60 quad_perm:[2,3,0,1] row_mask:0xf bank_mask:0xf bound_ctrl:1
	v_add_f32_dpp v62, v62, v62 quad_perm:[2,3,0,1] row_mask:0xf bank_mask:0xf bound_ctrl:1
	v_add_f32_dpp v64, v64, v64 quad_perm:[2,3,0,1] row_mask:0xf bank_mask:0xf bound_ctrl:1
	v_add_f32_dpp v66, v66, v66 quad_perm:[2,3,0,1] row_mask:0xf bank_mask:0xf bound_ctrl:1
	v_pk_fma_f32 v[92:93], v[236:237], v[230:231], v[92:93] op_sel_hi:[0,1,1]
	v_add_f32_dpp v60, v60, v60 row_half_mirror row_mask:0xf bank_mask:0xf bound_ctrl:1
	v_add_f32_dpp v62, v62, v62 row_half_mirror row_mask:0xf bank_mask:0xf bound_ctrl:1
	v_add_f32_dpp v64, v64, v64 row_half_mirror row_mask:0xf bank_mask:0xf bound_ctrl:1
	v_add_f32_dpp v66, v66, v66 row_half_mirror row_mask:0xf bank_mask:0xf bound_ctrl:1
	v_add_f32_dpp v60, v60, v60 row_mirror row_mask:0xf bank_mask:0xf bound_ctrl:1
	v_add_f32_dpp v62, v62, v62 row_mirror row_mask:0xf bank_mask:0xf bound_ctrl:1
	v_add_f32_dpp v64, v64, v64 row_mirror row_mask:0xf bank_mask:0xf bound_ctrl:1
	v_add_f32_dpp v66, v66, v66 row_mirror row_mask:0xf bank_mask:0xf bound_ctrl:1
	v_pk_fma_f32 v[94:95], v[224:225], v[60:61], v[94:95] op_sel_hi:[1,0,1] neg_lo:[1,0,0] neg_hi:[1,0,0]
	v_pk_fma_f32 v[92:93], v[226:227], v[60:61], v[92:93] op_sel_hi:[1,0,1] neg_lo:[1,0,0] neg_hi:[1,0,0]
	v_pk_mul_f32 v[238:239], v[224:225], v[62:63] op_sel_hi:[1,0]
	v_pk_mul_f32 v[240:241], v[226:227], v[62:63] op_sel_hi:[1,0]
	v_cndmask_b32_dpp v72, v72, v64, vcc row_shr:1 row_mask:0xf bank_mask:0xf bound_ctrl:1
	v_cndmask_b32_dpp v73, v73, v66, vcc row_shr:1 row_mask:0xf bank_mask:0xf bound_ctrl:1
	v_pk_mul_f32 v[64:65], v[232:233], v[94:95]
	v_pk_fma_f32 v[88:89], v[88:89], v[216:217], v[238:239] neg_lo:[0,0,1] neg_hi:[0,0,1]
	v_pk_fma_f32 v[90:91], v[90:91], v[218:219], v[240:241] neg_lo:[0,0,1] neg_hi:[0,0,1]
	v_pk_fma_f32 v[64:65], v[234:235], v[92:93], v[64:65]
	v_pk_mul_f32 v[66:67], v[232:233], v[88:89]
	v_pk_fma_f32 v[66:67], v[234:235], v[90:91], v[66:67]
	ds_read_b128 v[148:151], v74 offset:28672
	ds_read_b128 v[144:147], v74 offset:28416
	ds_read_b128 v[156:159], v74 offset:29184
	ds_read_b32 v96, v75 offset:29696
	ds_read_b128 v[152:155], v74 offset:28928
	ds_read_b128 v[160:163], v74 offset:29440
	s_waitcnt lgkmcnt(6)
	v_pk_mul_f32 v[60:61], v[94:95], v[126:127]
	v_pk_mul_f32 v[62:63], v[88:89], v[126:127]
	v_pk_fma_f32 v[60:61], v[92:93], v[128:129], v[60:61]
	v_pk_fma_f32 v[62:63], v[90:91], v[128:129], v[62:63]
	v_add_f32_e32 v64, v64, v65
	v_add_f32_e32 v66, v66, v67
	v_add_f32_e32 v60, v60, v61
	v_add_f32_e32 v62, v62, v63
	v_pk_mul_f32 v[94:95], v[94:95], v[122:123]
	v_pk_mul_f32 v[92:93], v[92:93], v[124:125]
	v_add_f32_dpp v60, v60, v60 quad_perm:[1,0,3,2] row_mask:0xf bank_mask:0xf bound_ctrl:1
	v_add_f32_dpp v62, v62, v62 quad_perm:[1,0,3,2] row_mask:0xf bank_mask:0xf bound_ctrl:1
	v_add_f32_dpp v64, v64, v64 quad_perm:[1,0,3,2] row_mask:0xf bank_mask:0xf bound_ctrl:1
	v_add_f32_dpp v66, v66, v66 quad_perm:[1,0,3,2] row_mask:0xf bank_mask:0xf bound_ctrl:1
	v_pk_fma_f32 v[94:95], v[142:143], v[134:135], v[94:95] op_sel_hi:[0,1,1]
	v_add_f32_dpp v60, v60, v60 quad_perm:[2,3,0,1] row_mask:0xf bank_mask:0xf bound_ctrl:1
	v_add_f32_dpp v62, v62, v62 quad_perm:[2,3,0,1] row_mask:0xf bank_mask:0xf bound_ctrl:1
	v_add_f32_dpp v64, v64, v64 quad_perm:[2,3,0,1] row_mask:0xf bank_mask:0xf bound_ctrl:1
	v_add_f32_dpp v66, v66, v66 quad_perm:[2,3,0,1] row_mask:0xf bank_mask:0xf bound_ctrl:1
	v_pk_fma_f32 v[92:93], v[142:143], v[136:137], v[92:93] op_sel_hi:[0,1,1]
	v_add_f32_dpp v60, v60, v60 row_half_mirror row_mask:0xf bank_mask:0xf bound_ctrl:1
	v_add_f32_dpp v62, v62, v62 row_half_mirror row_mask:0xf bank_mask:0xf bound_ctrl:1
	v_add_f32_dpp v64, v64, v64 row_half_mirror row_mask:0xf bank_mask:0xf bound_ctrl:1
	v_add_f32_dpp v66, v66, v66 row_half_mirror row_mask:0xf bank_mask:0xf bound_ctrl:1
	v_add_f32_dpp v60, v60, v60 row_mirror row_mask:0xf bank_mask:0xf bound_ctrl:1
	v_add_f32_dpp v62, v62, v62 row_mirror row_mask:0xf bank_mask:0xf bound_ctrl:1
	v_add_f32_dpp v64, v64, v64 row_mirror row_mask:0xf bank_mask:0xf bound_ctrl:1
	v_add_f32_dpp v66, v66, v66 row_mirror row_mask:0xf bank_mask:0xf bound_ctrl:1
	v_pk_fma_f32 v[94:95], v[130:131], v[60:61], v[94:95] op_sel_hi:[1,0,1] neg_lo:[1,0,0] neg_hi:[1,0,0]
	v_pk_fma_f32 v[92:93], v[132:133], v[60:61], v[92:93] op_sel_hi:[1,0,1] neg_lo:[1,0,0] neg_hi:[1,0,0]
	v_pk_mul_f32 v[238:239], v[130:131], v[62:63] op_sel_hi:[1,0]
	v_pk_mul_f32 v[240:241], v[132:133], v[62:63] op_sel_hi:[1,0]
	v_cndmask_b32_dpp v72, v72, v64, vcc row_shr:1 row_mask:0xf bank_mask:0xf bound_ctrl:1
	v_cndmask_b32_dpp v73, v73, v66, vcc row_shr:1 row_mask:0xf bank_mask:0xf bound_ctrl:1
	v_pk_mul_f32 v[64:65], v[138:139], v[94:95]
	v_pk_fma_f32 v[88:89], v[88:89], v[122:123], v[238:239] neg_lo:[0,0,1] neg_hi:[0,0,1]
	v_pk_fma_f32 v[90:91], v[90:91], v[124:125], v[240:241] neg_lo:[0,0,1] neg_hi:[0,0,1]
	v_pk_fma_f32 v[64:65], v[140:141], v[92:93], v[64:65]
	v_pk_mul_f32 v[66:67], v[138:139], v[88:89]
	v_pk_fma_f32 v[66:67], v[140:141], v[90:91], v[66:67]
	ds_read_b128 v[220:223], v74 offset:30208
	ds_read_b128 v[216:219], v74 offset:29952
	ds_read_b128 v[228:231], v74 offset:30720
	ds_read_b32 v236, v75 offset:31232
	ds_read_b128 v[224:227], v74 offset:30464
	ds_read_b128 v[232:235], v74 offset:30976
	s_waitcnt lgkmcnt(6)
; template <bool DUAL>
; __device__ __forceinline__ void rwkv_tile(const Params& p, int l, int tile, unsigned char* smem) {
;     ...
;       for (int i = 0; i < 32; ++i) {
;         const int inx = (i + 1) & 31;
;         const float4 nw4 = *(const float4*)(rp + inx * 384), nkk4 = *(const float4*)(rp + inx * 384 + 64), nkb4 = *(const float4*)(rp + inx * 384 + 128);
;         const float4 nkd4 = *(const float4*)(rp + inx * 384 + 192), nr4 = *(const float4*)(rp + inx * 384 + 256);
;         const float nv = vp[inx * 384];
;         v2f t = sA * (v2f){kk4.x, kk4.y};
;         t = sB * (v2f){kk4.z, kk4.w} + t;
;         float sa = t.x + t.y, ia = 0.f;
;         if (DUAL) {
;           v2f ti = iA * (v2f){kk4.x, kk4.y};
;           ti = iB * (v2f){kk4.z, kk4.w} + ti;
;           ia = ti.x + ti.y;
;           sa += dppf<0xB1>(sa); ia += dppf<0xB1>(ia);
;           sa += dppf<0x4E>(sa); ia += dppf<0x4E>(ia);
;           sa += dppf<0x141>(sa); ia += dppf<0x141>(ia);
;           sa += dppf<0x140>(sa); ia += dppf<0x140>(ia);
;         } else {
;           sa = sum16(sa);
;         }
;         v2f cA = sA * (v2f){w4.x, w4.y} + (v2f){kd4.x, kd4.y} * v;
;         v2f cB = sB * (v2f){w4.z, w4.w} + (v2f){kd4.z, kd4.w} * v;
;         sA = cA - (v2f){kb4.x, kb4.y} * sa;
;         sB = cB - (v2f){kb4.z, kb4.w} * sa;
;         v2f u = sA * (v2f){r4.x, r4.y};
;         u = sB * (v2f){r4.z, r4.w} + u;
;         float y = u.x + u.y, g = 0.f;
;         if (DUAL) {
;           iA = iA * (v2f){w4.x, w4.y} - (v2f){kb4.x, kb4.y} * ia;
;           iB = iB * (v2f){w4.z, w4.w} - (v2f){kb4.z, kb4.w} * ia;
;           v2f ui = iA * (v2f){r4.x, r4.y};
;           ui = iB * (v2f){r4.z, r4.w} + ui;
;           g = ui.x + ui.y;
;           y += dppf<0xB1>(y); g += dppf<0xB1>(g);
;           y += dppf<0x4E>(y); g += dppf<0x4E>(g);
;           y += dppf<0x141>(y); g += dppf<0x141>(g);
;           y += dppf<0x140>(y); g += dppf<0x140>(g);
	v_pk_mul_f32 v[60:61], v[94:95], v[148:149]
	v_pk_mul_f32 v[62:63], v[88:89], v[148:149]
	v_pk_fma_f32 v[60:61], v[92:93], v[150:151], v[60:61]
	v_pk_fma_f32 v[62:63], v[90:91], v[150:151], v[62:63]
	v_add_f32_e32 v64, v64, v65
	v_add_f32_e32 v66, v66, v67
	v_add_f32_e32 v60, v60, v61
	v_add_f32_e32 v62, v62, v63
	v_pk_mul_f32 v[94:95], v[94:95], v[144:145]
	v_pk_mul_f32 v[92:93], v[92:93], v[146:147]
	v_add_f32_dpp v60, v60, v60 quad_perm:[1,0,3,2] row_mask:0xf bank_mask:0xf bound_ctrl:1
	v_add_f32_dpp v62, v62, v62 quad_perm:[1,0,3,2] row_mask:0xf bank_mask:0xf bound_ctrl:1
	v_add_f32_dpp v64, v64, v64 quad_perm:[1,0,3,2] row_mask:0xf bank_mask:0xf bound_ctrl:1
	v_add_f32_dpp v66, v66, v66 quad_perm:[1,0,3,2] row_mask:0xf bank_mask:0xf bound_ctrl:1
	v_pk_fma_f32 v[94:95], v[96:97], v[156:157], v[94:95] op_sel_hi:[0,1,1]
	v_add_f32_dpp v60, v60, v60 quad_perm:[2,3,0,1] row_mask:0xf bank_mask:0xf bound_ctrl:1
	v_add_f32_dpp v62, v62, v62 quad_perm:[2,3,0,1] row_mask:0xf bank_mask:0xf bound_ctrl:1
	v_add_f32_dpp v64, v64, v64 quad_perm:[2,3,0,1] row_mask:0xf bank_mask:0xf bound_ctrl:1
	v_add_f32_dpp v66, v66, v66 quad_perm:[2,3,0,1] row_mask:0xf bank_mask:0xf bound_ctrl:1
	v_pk_fma_f32 v[92:93], v[96:97], v[158:159], v[92:93] op_sel_hi:[0,1,1]
	v_add_f32_dpp v60, v60, v60 row_half_mirror row_mask:0xf bank_mask:0xf bound_ctrl:1
	v_add_f32_dpp v62, v62, v62 row_half_mirror row_mask:0xf bank_mask:0xf bound_ctrl:1
	v_add_f32_dpp v64, v64, v64 row_half_mirror row_mask:0xf bank_mask:0xf bound_ctrl:1
	v_add_f32_dpp v66, v66, v66 row_half_mirror row_mask:0xf bank_mask:0xf bound_ctrl:1
	v_add_f32_dpp v60, v60, v60 row_mirror row_mask:0xf bank_mask:0xf bound_ctrl:1
	v_add_f32_dpp v62, v62, v62 row_mirror row_mask:0xf bank_mask:0xf bound_ctrl:1
	v_add_f32_dpp v64, v64, v64 row_mirror row_mask:0xf bank_mask:0xf bound_ctrl:1
	v_add_f32_dpp v66, v66, v66 row_mirror row_mask:0xf bank_mask:0xf bound_ctrl:1
	v_pk_fma_f32 v[94:95], v[152:153], v[60:61], v[94:95] op_sel_hi:[1,0,1] neg_lo:[1,0,0] neg_hi:[1,0,0]
	v_pk_fma_f32 v[92:93], v[154:155], v[60:61], v[92:93] op_sel_hi:[1,0,1] neg_lo:[1,0,0] neg_hi:[1,0,0]
	v_pk_mul_f32 v[238:239], v[152:153], v[62:63] op_sel_hi:[1,0]
	v_pk_mul_f32 v[240:241], v[154:155], v[62:63] op_sel_hi:[1,0]
	v_cndmask_b32_dpp v72, v72, v64, vcc row_shr:1 row_mask:0xf bank_mask:0xf bound_ctrl:1
	v_cndmask_b32_dpp v73, v73, v66, vcc row_shr:1 row_mask:0xf bank_mask:0xf bound_ctrl:1
	v_pk_mul_f32 v[64:65], v[160:161], v[94:95]
	v_pk_fma_f32 v[88:89], v[88:89], v[144:145], v[238:239] neg_lo:[0,0,1] neg_hi:[0,0,1]
	v_pk_fma_f32 v[90:91], v[90:91], v[146:147], v[240:241] neg_lo:[0,0,1] neg_hi:[0,0,1]
	v_pk_fma_f32 v[64:65], v[162:163], v[92:93], v[64:65]
	v_pk_mul_f32 v[66:67], v[160:161], v[88:89]
	v_pk_fma_f32 v[66:67], v[162:163], v[90:91], v[66:67]
	ds_read_b128 v[126:129], v74 offset:31744
	ds_read_b128 v[122:125], v74 offset:31488
	ds_read_b128 v[134:137], v74 offset:32256
	ds_read_b32 v142, v75 offset:32768
	ds_read_b128 v[130:133], v74 offset:32000
	ds_read_b128 v[138:141], v74 offset:32512
	s_waitcnt lgkmcnt(6)
	v_pk_mul_f32 v[60:61], v[94:95], v[220:221]
	v_pk_mul_f32 v[62:63], v[88:89], v[220:221]
	v_pk_fma_f32 v[60:61], v[92:93], v[222:223], v[60:61]
	v_pk_fma_f32 v[62:63], v[90:91], v[222:223], v[62:63]
	v_add_f32_e32 v64, v64, v65
	v_add_f32_e32 v66, v66, v67
	v_add_f32_e32 v60, v60, v61
	v_add_f32_e32 v62, v62, v63
	v_pk_mul_f32 v[94:95], v[94:95], v[216:217]
	v_pk_mul_f32 v[92:93], v[92:93], v[218:219]
	v_add_f32_dpp v60, v60, v60 quad_perm:[1,0,3,2] row_mask:0xf bank_mask:0xf bound_ctrl:1
	v_add_f32_dpp v62, v62, v62 quad_perm:[1,0,3,2] row_mask:0xf bank_mask:0xf bound_ctrl:1
	v_add_f32_dpp v64, v64, v64 quad_perm:[1,0,3,2] row_mask:0xf bank_mask:0xf bound_ctrl:1
	v_add_f32_dpp v66, v66, v66 quad_perm:[1,0,3,2] row_mask:0xf bank_mask:0xf bound_ctrl:1
	v_pk_fma_f32 v[94:95], v[236:237], v[228:229], v[94:95] op_sel_hi:[0,1,1]
	v_add_f32_dpp v60, v60, v60 quad_perm:[2,3,0,1] row_mask:0xf bank_mask:0xf bound_ctrl:1
	v_add_f32_dpp v62, v62, v62 quad_perm:[2,3,0,1] row_mask:0xf bank_mask:0xf bound_ctrl:1
	v_add_f32_dpp v64, v64, v64 quad_perm:[2,3,0,1] row_mask:0xf bank_mask:0xf bound_ctrl:1
	v_add_f32_dpp v66, v66, v66 quad_perm:[2,3,0,1] row_mask:0xf bank_mask:0xf bound_ctrl:1
	v_pk_fma_f32 v[92:93], v[236:237], v[230:231], v[92:93] op_sel_hi:[0,1,1]
	v_add_f32_dpp v60, v60, v60 row_half_mirror row_mask:0xf bank_mask:0xf bound_ctrl:1
	v_add_f32_dpp v62, v62, v62 row_half_mirror row_mask:0xf bank_mask:0xf bound_ctrl:1
	v_add_f32_dpp v64, v64, v64 row_half_mirror row_mask:0xf bank_mask:0xf bound_ctrl:1
	v_add_f32_dpp v66, v66, v66 row_half_mirror row_mask:0xf bank_mask:0xf bound_ctrl:1
	v_add_f32_dpp v60, v60, v60 row_mirror row_mask:0xf bank_mask:0xf bound_ctrl:1
	v_add_f32_dpp v62, v62, v62 row_mirror row_mask:0xf bank_mask:0xf bound_ctrl:1
	v_add_f32_dpp v64, v64, v64 row_mirror row_mask:0xf bank_mask:0xf bound_ctrl:1
	v_add_f32_dpp v66, v66, v66 row_mirror row_mask:0xf bank_mask:0xf bound_ctrl:1
	v_pk_fma_f32 v[94:95], v[224:225], v[60:61], v[94:95] op_sel_hi:[1,0,1] neg_lo:[1,0,0] neg_hi:[1,0,0]
	v_pk_fma_f32 v[92:93], v[226:227], v[60:61], v[92:93] op_sel_hi:[1,0,1] neg_lo:[1,0,0] neg_hi:[1,0,0]
	v_pk_mul_f32 v[238:239], v[224:225], v[62:63] op_sel_hi:[1,0]
	v_pk_mul_f32 v[240:241], v[226:227], v[62:63] op_sel_hi:[1,0]
	v_cndmask_b32_dpp v72, v72, v64, vcc row_shr:1 row_mask:0xf bank_mask:0xf bound_ctrl:1
	v_cndmask_b32_dpp v73, v73, v66, vcc row_shr:1 row_mask:0xf bank_mask:0xf bound_ctrl:1
	v_pk_mul_f32 v[64:65], v[232:233], v[94:95]
	v_pk_fma_f32 v[88:89], v[88:89], v[216:217], v[238:239] neg_lo:[0,0,1] neg_hi:[0,0,1]
	v_pk_fma_f32 v[90:91], v[90:91], v[218:219], v[240:241] neg_lo:[0,0,1] neg_hi:[0,0,1]
	v_pk_fma_f32 v[64:65], v[234:235], v[92:93], v[64:65]
	v_pk_mul_f32 v[66:67], v[232:233], v[88:89]
	v_pk_fma_f32 v[66:67], v[234:235], v[90:91], v[66:67]
	ds_read_b128 v[148:151], v74 offset:33280
	ds_read_b128 v[144:147], v74 offset:33024
	ds_read_b128 v[156:159], v74 offset:33792
	ds_read_b32 v96, v75 offset:34304
	ds_read_b128 v[152:155], v74 offset:33536
	ds_read_b128 v[160:163], v74 offset:34048
	s_waitcnt lgkmcnt(6)
; template <bool DUAL>
; __device__ __forceinline__ void rwkv_tile(const Params& p, int l, int tile, unsigned char* smem) {
;     ...
;       for (int i = 0; i < 32; ++i) {
;         const int inx = (i + 1) & 31;
;         const float4 nw4 = *(const float4*)(rp + inx * 384), nkk4 = *(const float4*)(rp + inx * 384 + 64), nkb4 = *(const float4*)(rp + inx * 384 + 128);
;         const float4 nkd4 = *(const float4*)(rp + inx * 384 + 192), nr4 = *(const float4*)(rp + inx * 384 + 256);
;         const float nv = vp[inx * 384];
;         v2f t = sA * (v2f){kk4.x, kk4.y};
;         t = sB * (v2f){kk4.z, kk4.w} + t;
;         float sa = t.x + t.y, ia = 0.f;
;         if (DUAL) {
;           v2f ti = iA * (v2f){kk4.x, kk4.y};
;           ti = iB * (v2f){kk4.z, kk4.w} + ti;
;           ia = ti.x + ti.y;
;           sa += dppf<0xB1>(sa); ia += dppf<0xB1>(ia);
;           sa += dppf<0x4E>(sa); ia += dppf<0x4E>(ia);
;           sa += dppf<0x141>(sa); ia += dppf<0x141>(ia);
;           sa += dppf<0x140>(sa); ia += dppf<0x140>(ia);
;         } else {
;           sa = sum16(sa);
;         }
;         v2f cA = sA * (v2f){w4.x, w4.y} + (v2f){kd4.x, kd4.y} * v;
;         v2f cB = sB * (v2f){w4.z, w4.w} + (v2f){kd4.z, kd4.w} * v;
;         sA = cA - (v2f){kb4.x, kb4.y} * sa;
;         sB = cB - (v2f){kb4.z, kb4.w} * sa;
;         v2f u = sA * (v2f){r4.x, r4.y};
;         u = sB * (v2f){r4.z, r4.w} + u;
;         float y = u.x + u.y, g = 0.f;
;         if (DUAL) {
;           iA = iA * (v2f){w4.x, w4.y} - (v2f){kb4.x, kb4.y} * ia;
;           iB = iB * (v2f){w4.z, w4.w} - (v2f){kb4.z, kb4.w} * ia;
;           v2f ui = iA * (v2f){r4.x, r4.y};
;           ui = iB * (v2f){r4.z, r4.w} + ui;
;           g = ui.x + ui.y;
;           y += dppf<0xB1>(y); g += dppf<0xB1>(g);
;           y += dppf<0x4E>(y); g += dppf<0x4E>(g);
;           y += dppf<0x141>(y); g += dppf<0x141>(g);
;           y += dppf<0x140>(y); g += dppf<0x140>(g);
	v_pk_mul_f32 v[60:61], v[94:95], v[126:127]
	v_pk_mul_f32 v[62:63], v[88:89], v[126:127]
	v_pk_fma_f32 v[60:61], v[92:93], v[128:129], v[60:61]
	v_pk_fma_f32 v[62:63], v[90:91], v[128:129], v[62:63]
	v_add_f32_e32 v64, v64, v65
	v_add_f32_e32 v66, v66, v67
	v_add_f32_e32 v60, v60, v61
	v_add_f32_e32 v62, v62, v63
	v_pk_mul_f32 v[94:95], v[94:95], v[122:123]
	v_pk_mul_f32 v[92:93], v[92:93], v[124:125]
	v_add_f32_dpp v60, v60, v60 quad_perm:[1,0,3,2] row_mask:0xf bank_mask:0xf bound_ctrl:1
	v_add_f32_dpp v62, v62, v62 quad_perm:[1,0,3,2] row_mask:0xf bank_mask:0xf bound_ctrl:1
	v_add_f32_dpp v64, v64, v64 quad_perm:[1,0,3,2] row_mask:0xf bank_mask:0xf bound_ctrl:1
	v_add_f32_dpp v66, v66, v66 quad_perm:[1,0,3,2] row_mask:0xf bank_mask:0xf bound_ctrl:1
	v_pk_fma_f32 v[94:95], v[142:143], v[134:135], v[94:95] op_sel_hi:[0,1,1]
	v_add_f32_dpp v60, v60, v60 quad_perm:[2,3,0,1] row_mask:0xf bank_mask:0xf bound_ctrl:1
	v_add_f32_dpp v62, v62, v62 quad_perm:[2,3,0,1] row_mask:0xf bank_mask:0xf bound_ctrl:1
	v_add_f32_dpp v64, v64, v64 quad_perm:[2,3,0,1] row_mask:0xf bank_mask:0xf bound_ctrl:1
	v_add_f32_dpp v66, v66, v66 quad_perm:[2,3,0,1] row_mask:0xf bank_mask:0xf bound_ctrl:1
	v_pk_fma_f32 v[92:93], v[142:143], v[136:137], v[92:93] op_sel_hi:[0,1,1]
	v_add_f32_dpp v60, v60, v60 row_half_mirror row_mask:0xf bank_mask:0xf bound_ctrl:1
	v_add_f32_dpp v62, v62, v62 row_half_mirror row_mask:0xf bank_mask:0xf bound_ctrl:1
	v_add_f32_dpp v64, v64, v64 row_half_mirror row_mask:0xf bank_mask:0xf bound_ctrl:1
	v_add_f32_dpp v66, v66, v66 row_half_mirror row_mask:0xf bank_mask:0xf bound_ctrl:1
	v_add_f32_dpp v60, v60, v60 row_mirror row_mask:0xf bank_mask:0xf bound_ctrl:1
	v_add_f32_dpp v62, v62, v62 row_mirror row_mask:0xf bank_mask:0xf bound_ctrl:1
	v_add_f32_dpp v64, v64, v64 row_mirror row_mask:0xf bank_mask:0xf bound_ctrl:1
	v_add_f32_dpp v66, v66, v66 row_mirror row_mask:0xf bank_mask:0xf bound_ctrl:1
	v_pk_fma_f32 v[94:95], v[130:131], v[60:61], v[94:95] op_sel_hi:[1,0,1] neg_lo:[1,0,0] neg_hi:[1,0,0]
	v_pk_fma_f32 v[92:93], v[132:133], v[60:61], v[92:93] op_sel_hi:[1,0,1] neg_lo:[1,0,0] neg_hi:[1,0,0]
	v_pk_mul_f32 v[238:239], v[130:131], v[62:63] op_sel_hi:[1,0]
	v_pk_mul_f32 v[240:241], v[132:133], v[62:63] op_sel_hi:[1,0]
	v_cndmask_b32_dpp v72, v72, v64, vcc row_shr:1 row_mask:0xf bank_mask:0xf bound_ctrl:1
	v_cndmask_b32_dpp v73, v73, v66, vcc row_shr:1 row_mask:0xf bank_mask:0xf bound_ctrl:1
	s_cmp_eq_u32 s55, 2
	s_cbranch_scc1 .Lrw_du_st0
.Lrw_du_back:
	v_pk_mul_f32 v[64:65], v[138:139], v[94:95]
	v_pk_fma_f32 v[88:89], v[88:89], v[122:123], v[238:239] neg_lo:[0,0,1] neg_hi:[0,0,1]
	v_pk_fma_f32 v[90:91], v[90:91], v[124:125], v[240:241] neg_lo:[0,0,1] neg_hi:[0,0,1]
	v_pk_fma_f32 v[64:65], v[140:141], v[92:93], v[64:65]
	v_pk_mul_f32 v[66:67], v[138:139], v[88:89]
	v_pk_fma_f32 v[66:67], v[140:141], v[90:91], v[66:67]
	ds_read_b128 v[220:223], v74 offset:34816
	ds_read_b128 v[216:219], v74 offset:34560
	ds_read_b128 v[228:231], v74 offset:35328
	ds_read_b32 v236, v75 offset:35840
	ds_read_b128 v[224:227], v74 offset:35072
	ds_read_b128 v[232:235], v74 offset:35584
	s_waitcnt lgkmcnt(6)
	v_pk_mul_f32 v[60:61], v[94:95], v[148:149]
	v_pk_mul_f32 v[62:63], v[88:89], v[148:149]
	v_pk_fma_f32 v[60:61], v[92:93], v[150:151], v[60:61]
	v_pk_fma_f32 v[62:63], v[90:91], v[150:151], v[62:63]
	v_add_f32_e32 v64, v64, v65
	v_add_f32_e32 v66, v66, v67
	v_add_f32_e32 v60, v60, v61
	v_add_f32_e32 v62, v62, v63
	v_pk_mul_f32 v[94:95], v[94:95], v[144:145]
	v_pk_mul_f32 v[92:93], v[92:93], v[146:147]
	v_add_f32_dpp v60, v60, v60 quad_perm:[1,0,3,2] row_mask:0xf bank_mask:0xf bound_ctrl:1
	v_add_f32_dpp v62, v62, v62 quad_perm:[1,0,3,2] row_mask:0xf bank_mask:0xf bound_ctrl:1
	v_add_f32_dpp v64, v64, v64 quad_perm:[1,0,3,2] row_mask:0xf bank_mask:0xf bound_ctrl:1
	v_add_f32_dpp v66, v66, v66 quad_perm:[1,0,3,2] row_mask:0xf bank_mask:0xf bound_ctrl:1
	v_pk_fma_f32 v[94:95], v[96:97], v[156:157], v[94:95] op_sel_hi:[0,1,1]
	v_add_f32_dpp v60, v60, v60 quad_perm:[2,3,0,1] row_mask:0xf bank_mask:0xf bound_ctrl:1
	v_add_f32_dpp v62, v62, v62 quad_perm:[2,3,0,1] row_mask:0xf bank_mask:0xf bound_ctrl:1
	v_add_f32_dpp v64, v64, v64 quad_perm:[2,3,0,1] row_mask:0xf bank_mask:0xf bound_ctrl:1
	v_add_f32_dpp v66, v66, v66 quad_perm:[2,3,0,1] row_mask:0xf bank_mask:0xf bound_ctrl:1
	v_pk_fma_f32 v[92:93], v[96:97], v[158:159], v[92:93] op_sel_hi:[0,1,1]
	v_add_f32_dpp v60, v60, v60 row_half_mirror row_mask:0xf bank_mask:0xf bound_ctrl:1
	v_add_f32_dpp v62, v62, v62 row_half_mirror row_mask:0xf bank_mask:0xf bound_ctrl:1
	v_add_f32_dpp v64, v64, v64 row_half_mirror row_mask:0xf bank_mask:0xf bound_ctrl:1
	v_add_f32_dpp v66, v66, v66 row_half_mirror row_mask:0xf bank_mask:0xf bound_ctrl:1
	v_add_f32_dpp v60, v60, v60 row_mirror row_mask:0xf bank_mask:0xf bound_ctrl:1
	v_add_f32_dpp v62, v62, v62 row_mirror row_mask:0xf bank_mask:0xf bound_ctrl:1
	v_add_f32_dpp v64, v64, v64 row_mirror row_mask:0xf bank_mask:0xf bound_ctrl:1
	v_add_f32_dpp v66, v66, v66 row_mirror row_mask:0xf bank_mask:0xf bound_ctrl:1
	v_pk_fma_f32 v[94:95], v[152:153], v[60:61], v[94:95] op_sel_hi:[1,0,1] neg_lo:[1,0,0] neg_hi:[1,0,0]
	v_pk_fma_f32 v[92:93], v[154:155], v[60:61], v[92:93] op_sel_hi:[1,0,1] neg_lo:[1,0,0] neg_hi:[1,0,0]
	v_pk_mul_f32 v[238:239], v[152:153], v[62:63] op_sel_hi:[1,0]
	v_pk_mul_f32 v[240:241], v[154:155], v[62:63] op_sel_hi:[1,0]
	v_cndmask_b32_dpp v72, v72, v64, vcc row_shr:1 row_mask:0xf bank_mask:0xf bound_ctrl:1
	v_cndmask_b32_dpp v73, v73, v66, vcc row_shr:1 row_mask:0xf bank_mask:0xf bound_ctrl:1
	v_pk_mul_f32 v[64:65], v[160:161], v[94:95]
	v_pk_fma_f32 v[88:89], v[88:89], v[144:145], v[238:239] neg_lo:[0,0,1] neg_hi:[0,0,1]
	v_pk_fma_f32 v[90:91], v[90:91], v[146:147], v[240:241] neg_lo:[0,0,1] neg_hi:[0,0,1]
	v_pk_fma_f32 v[64:65], v[162:163], v[92:93], v[64:65]
	v_pk_mul_f32 v[66:67], v[160:161], v[88:89]
	v_pk_fma_f32 v[66:67], v[162:163], v[90:91], v[66:67]
	ds_read_b128 v[126:129], v74 offset:36352
	ds_read_b128 v[122:125], v74 offset:36096
	ds_read_b128 v[134:137], v74 offset:36864
	ds_read_b32 v142, v75 offset:37376
	ds_read_b128 v[130:133], v74 offset:36608
	ds_read_b128 v[138:141], v74 offset:37120
	v_add_u32_e32 v74, 0x2400, v74
	v_add_u32_e32 v75, 0x2400, v75
	s_add_i32 s55, s55, 1
	s_cmp_lg_u32 s55, 5
	s_cbranch_scc1 .Lrw_du_loop
; template <bool DUAL>
; __device__ __forceinline__ void rwkv_tile(const Params& p, int l, int tile, unsigned char* smem) {
;     ...
;       for (int i = 0; i < 32; ++i) {
;         const int inx = (i + 1) & 31;
;         const float4 nw4 = *(const float4*)(rp + inx * 384), nkk4 = *(const float4*)(rp + inx * 384 + 64), nkb4 = *(const float4*)(rp + inx * 384 + 128);
;         const float4 nkd4 = *(const float4*)(rp + inx * 384 + 192), nr4 = *(const float4*)(rp + inx * 384 + 256);
;         const float nv = vp[inx * 384];
;         v2f t = sA * (v2f){kk4.x, kk4.y};
;         t = sB * (v2f){kk4.z, kk4.w} + t;
;         float sa = t.x + t.y, ia = 0.f;
;         if (DUAL) {
;           v2f ti = iA * (v2f){kk4.x, kk4.y};
;           ti = iB * (v2f){kk4.z, kk4.w} + ti;
;           ia = ti.x + ti.y;
;           sa += dppf<0xB1>(sa); ia += dppf<0xB1>(ia);
;           sa += dppf<0x4E>(sa); ia += dppf<0x4E>(ia);
;           sa += dppf<0x141>(sa); ia += dppf<0x141>(ia);
;           sa += dppf<0x140>(sa); ia += dppf<0x140>(ia);
;         } else {
;           sa = sum16(sa);
;         }
;         v2f cA = sA * (v2f){w4.x, w4.y} + (v2f){kd4.x, kd4.y} * v;
;         v2f cB = sB * (v2f){w4.z, w4.w} + (v2f){kd4.z, kd4.w} * v;
;         sA = cA - (v2f){kb4.x, kb4.y} * sa;
;         sB = cB - (v2f){kb4.z, kb4.w} * sa;
;         v2f u = sA * (v2f){r4.x, r4.y};
;         u = sB * (v2f){r4.z, r4.w} + u;
;         float y = u.x + u.y, g = 0.f;
;         if (DUAL) {
;           iA = iA * (v2f){w4.x, w4.y} - (v2f){kb4.x, kb4.y} * ia;
;           iB = iB * (v2f){w4.z, w4.w} - (v2f){kb4.z, kb4.w} * ia;
;           v2f ui = iA * (v2f){r4.x, r4.y};
;           ui = iB * (v2f){r4.z, r4.w} + ui;
;           g = ui.x + ui.y;
;           y += dppf<0xB1>(y); g += dppf<0xB1>(g);
;           y += dppf<0x4E>(y); g += dppf<0x4E>(g);
;           y += dppf<0x141>(y); g += dppf<0x141>(g);
;           y += dppf<0x140>(y); g += dppf<0x140>(g);
	s_waitcnt lgkmcnt(6)
	v_pk_mul_f32 v[60:61], v[94:95], v[220:221]
	v_pk_mul_f32 v[62:63], v[88:89], v[220:221]
	v_pk_fma_f32 v[60:61], v[92:93], v[222:223], v[60:61]
	v_pk_fma_f32 v[62:63], v[90:91], v[222:223], v[62:63]
	v_add_f32_e32 v64, v64, v65
	v_add_f32_e32 v66, v66, v67
	v_add_f32_e32 v60, v60, v61
	v_add_f32_e32 v62, v62, v63
	v_pk_mul_f32 v[94:95], v[94:95], v[216:217]
	v_pk_mul_f32 v[92:93], v[92:93], v[218:219]
	v_add_f32_dpp v60, v60, v60 quad_perm:[1,0,3,2] row_mask:0xf bank_mask:0xf bound_ctrl:1
	v_add_f32_dpp v62, v62, v62 quad_perm:[1,0,3,2] row_mask:0xf bank_mask:0xf bound_ctrl:1
	v_add_f32_dpp v64, v64, v64 quad_perm:[1,0,3,2] row_mask:0xf bank_mask:0xf bound_ctrl:1
	v_add_f32_dpp v66, v66, v66 quad_perm:[1,0,3,2] row_mask:0xf bank_mask:0xf bound_ctrl:1
	v_pk_fma_f32 v[94:95], v[236:237], v[228:229], v[94:95] op_sel_hi:[0,1,1]
	v_add_f32_dpp v60, v60, v60 quad_perm:[2,3,0,1] row_mask:0xf bank_mask:0xf bound_ctrl:1
	v_add_f32_dpp v62, v62, v62 quad_perm:[2,3,0,1] row_mask:0xf bank_mask:0xf bound_ctrl:1
	v_add_f32_dpp v64, v64, v64 quad_perm:[2,3,0,1] row_mask:0xf bank_mask:0xf bound_ctrl:1
	v_add_f32_dpp v66, v66, v66 quad_perm:[2,3,0,1] row_mask:0xf bank_mask:0xf bound_ctrl:1
	v_pk_fma_f32 v[92:93], v[236:237], v[230:231], v[92:93] op_sel_hi:[0,1,1]
	v_add_f32_dpp v60, v60, v60 row_half_mirror row_mask:0xf bank_mask:0xf bound_ctrl:1
	v_add_f32_dpp v62, v62, v62 row_half_mirror row_mask:0xf bank_mask:0xf bound_ctrl:1
	v_add_f32_dpp v64, v64, v64 row_half_mirror row_mask:0xf bank_mask:0xf bound_ctrl:1
	v_add_f32_dpp v66, v66, v66 row_half_mirror row_mask:0xf bank_mask:0xf bound_ctrl:1
	v_add_f32_dpp v60, v60, v60 row_mirror row_mask:0xf bank_mask:0xf bound_ctrl:1
	v_add_f32_dpp v62, v62, v62 row_mirror row_mask:0xf bank_mask:0xf bound_ctrl:1
	v_add_f32_dpp v64, v64, v64 row_mirror row_mask:0xf bank_mask:0xf bound_ctrl:1
	v_add_f32_dpp v66, v66, v66 row_mirror row_mask:0xf bank_mask:0xf bound_ctrl:1
	v_pk_fma_f32 v[94:95], v[224:225], v[60:61], v[94:95] op_sel_hi:[1,0,1] neg_lo:[1,0,0] neg_hi:[1,0,0]
	v_pk_fma_f32 v[92:93], v[226:227], v[60:61], v[92:93] op_sel_hi:[1,0,1] neg_lo:[1,0,0] neg_hi:[1,0,0]
	v_pk_mul_f32 v[238:239], v[224:225], v[62:63] op_sel_hi:[1,0]
	v_pk_mul_f32 v[240:241], v[226:227], v[62:63] op_sel_hi:[1,0]
	v_cndmask_b32_dpp v72, v72, v64, vcc row_shr:1 row_mask:0xf bank_mask:0xf bound_ctrl:1
	v_cndmask_b32_dpp v73, v73, v66, vcc row_shr:1 row_mask:0xf bank_mask:0xf bound_ctrl:1
	v_pk_mul_f32 v[64:65], v[232:233], v[94:95]
	v_pk_fma_f32 v[88:89], v[88:89], v[216:217], v[238:239] neg_lo:[0,0,1] neg_hi:[0,0,1]
	v_pk_fma_f32 v[90:91], v[90:91], v[218:219], v[240:241] neg_lo:[0,0,1] neg_hi:[0,0,1]
	v_pk_fma_f32 v[64:65], v[234:235], v[92:93], v[64:65]
	v_pk_mul_f32 v[66:67], v[232:233], v[88:89]
	v_pk_fma_f32 v[66:67], v[234:235], v[90:91], v[66:67]
	s_waitcnt lgkmcnt(0)
	v_pk_mul_f32 v[60:61], v[94:95], v[126:127]
	v_pk_mul_f32 v[62:63], v[88:89], v[126:127]
	v_pk_fma_f32 v[60:61], v[92:93], v[128:129], v[60:61]
	v_pk_fma_f32 v[62:63], v[90:91], v[128:129], v[62:63]
	v_add_f32_e32 v64, v64, v65
	v_add_f32_e32 v66, v66, v67
	v_add_f32_e32 v60, v60, v61
	v_add_f32_e32 v62, v62, v63
	v_pk_mul_f32 v[94:95], v[94:95], v[122:123]
	v_pk_mul_f32 v[92:93], v[92:93], v[124:125]
	v_add_f32_dpp v60, v60, v60 quad_perm:[1,0,3,2] row_mask:0xf bank_mask:0xf bound_ctrl:1
	v_add_f32_dpp v62, v62, v62 quad_perm:[1,0,3,2] row_mask:0xf bank_mask:0xf bound_ctrl:1
	v_add_f32_dpp v64, v64, v64 quad_perm:[1,0,3,2] row_mask:0xf bank_mask:0xf bound_ctrl:1
	v_add_f32_dpp v66, v66, v66 quad_perm:[1,0,3,2] row_mask:0xf bank_mask:0xf bound_ctrl:1
	v_pk_fma_f32 v[94:95], v[142:143], v[134:135], v[94:95] op_sel_hi:[0,1,1]
	v_add_f32_dpp v60, v60, v60 quad_perm:[2,3,0,1] row_mask:0xf bank_mask:0xf bound_ctrl:1
	v_add_f32_dpp v62, v62, v62 quad_perm:[2,3,0,1] row_mask:0xf bank_mask:0xf bound_ctrl:1
	v_add_f32_dpp v64, v64, v64 quad_perm:[2,3,0,1] row_mask:0xf bank_mask:0xf bound_ctrl:1
	v_add_f32_dpp v66, v66, v66 quad_perm:[2,3,0,1] row_mask:0xf bank_mask:0xf bound_ctrl:1
	v_pk_fma_f32 v[92:93], v[142:143], v[136:137], v[92:93] op_sel_hi:[0,1,1]
	v_add_f32_dpp v60, v60, v60 row_half_mirror row_mask:0xf bank_mask:0xf bound_ctrl:1
	v_add_f32_dpp v62, v62, v62 row_half_mirror row_mask:0xf bank_mask:0xf bound_ctrl:1
	v_add_f32_dpp v64, v64, v64 row_half_mirror row_mask:0xf bank_mask:0xf bound_ctrl:1
	v_add_f32_dpp v66, v66, v66 row_half_mirror row_mask:0xf bank_mask:0xf bound_ctrl:1
	v_add_f32_dpp v60, v60, v60 row_mirror row_mask:0xf bank_mask:0xf bound_ctrl:1
	v_add_f32_dpp v62, v62, v62 row_mirror row_mask:0xf bank_mask:0xf bound_ctrl:1
	v_add_f32_dpp v64, v64, v64 row_mirror row_mask:0xf bank_mask:0xf bound_ctrl:1
	v_add_f32_dpp v66, v66, v66 row_mirror row_mask:0xf bank_mask:0xf bound_ctrl:1
	v_pk_fma_f32 v[94:95], v[130:131], v[60:61], v[94:95] op_sel_hi:[1,0,1] neg_lo:[1,0,0] neg_hi:[1,0,0]
	v_pk_fma_f32 v[92:93], v[132:133], v[60:61], v[92:93] op_sel_hi:[1,0,1] neg_lo:[1,0,0] neg_hi:[1,0,0]
	v_pk_mul_f32 v[238:239], v[130:131], v[62:63] op_sel_hi:[1,0]
	v_pk_mul_f32 v[240:241], v[132:133], v[62:63] op_sel_hi:[1,0]
	v_cndmask_b32_dpp v72, v72, v64, vcc row_shr:1 row_mask:0xf bank_mask:0xf bound_ctrl:1
	v_cndmask_b32_dpp v73, v73, v66, vcc row_shr:1 row_mask:0xf bank_mask:0xf bound_ctrl:1
	v_pk_mul_f32 v[64:65], v[138:139], v[94:95]
	v_pk_fma_f32 v[88:89], v[88:89], v[122:123], v[238:239] neg_lo:[0,0,1] neg_hi:[0,0,1]
	v_pk_fma_f32 v[90:91], v[90:91], v[124:125], v[240:241] neg_lo:[0,0,1] neg_hi:[0,0,1]
	v_pk_fma_f32 v[64:65], v[140:141], v[92:93], v[64:65]
	v_pk_mul_f32 v[66:67], v[138:139], v[88:89]
	v_pk_fma_f32 v[66:67], v[140:141], v[90:91], v[66:67]
; __device__ __forceinline__ bf16_t f2bf(float f) { return (bf16_t)(pack2(f, 0.f) & 0xffffu); }
; template <bool DUAL>
; __device__ __forceinline__ void rwkv_tile(const Params& p, int l, int tile, unsigned char* smem) {
;     ...
;       for (int i = 0; i < 32; ++i) {
;         const int inx = (i + 1) & 31;
;         const float4 nw4 = *(const float4*)(rp + inx * 384), nkk4 = *(const float4*)(rp + inx * 384 + 64), nkb4 = *(const float4*)(rp + inx * 384 + 128);
;         const float4 nkd4 = *(const float4*)(rp + inx * 384 + 192), nr4 = *(const float4*)(rp + inx * 384 + 256);
;         const float nv = vp[inx * 384];
;         v2f t = sA * (v2f){kk4.x, kk4.y};
;         t = sB * (v2f){kk4.z, kk4.w} + t;
;         float sa = t.x + t.y, ia = 0.f;
;         if (DUAL) {
;           v2f ti = iA * (v2f){kk4.x, kk4.y};
;           ti = iB * (v2f){kk4.z, kk4.w} + ti;
;           ia = ti.x + ti.y;
;           sa += dppf<0xB1>(sa); ia += dppf<0xB1>(ia);
;           sa += dppf<0x4E>(sa); ia += dppf<0x4E>(ia);
;           sa += dppf<0x141>(sa); ia += dppf<0x141>(ia);
;           sa += dppf<0x140>(sa); ia += dppf<0x140>(ia);
;         } else {
;           sa = sum16(sa);
;         }
;         v2f cA = sA * (v2f){w4.x, w4.y} + (v2f){kd4.x, kd4.y} * v;
;         v2f cB = sB * (v2f){w4.z, w4.w} + (v2f){kd4.z, kd4.w} * v;
;         sA = cA - (v2f){kb4.x, kb4.y} * sa;
;         sB = cB - (v2f){kb4.z, kb4.w} * sa;
;         v2f u = sA * (v2f){r4.x, r4.y};
;         u = sB * (v2f){r4.z, r4.w} + u;
;         float y = u.x + u.y, g = 0.f;
;         if (DUAL) {
;           iA = iA * (v2f){w4.x, w4.y} - (v2f){kb4.x, kb4.y} * ia;
;     ...
;           y += dppf<0x140>(y); g += dppf<0x140>(g);
;           if (fr == (i & 15)) gkeep = g;
;         } else {
;           y = sum16(y);
;         }
;         if (fr == (i & 15)) ykeep = y;
;         if ((i & 15) == 15) {
;           const int ii = (i & 16) + fr;
;           const int ri = (d == 0) ? ii + 1 : 32 - ii;
;           const int pi = plo - 1 + ri;
;           p.yR[((size_t)d * TOK + rowbase + pi) * 256 + h * 64 + row] = f2bf(ykeep);
;           if (DUAL) p.GID[((size_t)(d * 4 + b) * NSEG1 + (cix - CSPLIT) * 32 + ii) * 256 + h * 64 + row] = f2bf(gkeep);
	v_add_f32_e32 v64, v64, v65
	v_add_f32_e32 v66, v66, v67
	s_nop 1
	v_add_f32_dpp v64, v64, v64 quad_perm:[1,0,3,2] row_mask:0xf bank_mask:0xf bound_ctrl:1
	v_add_f32_dpp v66, v66, v66 quad_perm:[1,0,3,2] row_mask:0xf bank_mask:0xf bound_ctrl:1
	s_nop 0
	v_add_f32_dpp v64, v64, v64 quad_perm:[2,3,0,1] row_mask:0xf bank_mask:0xf bound_ctrl:1
	v_add_f32_dpp v66, v66, v66 quad_perm:[2,3,0,1] row_mask:0xf bank_mask:0xf bound_ctrl:1
	s_nop 0
	v_add_f32_dpp v64, v64, v64 row_half_mirror row_mask:0xf bank_mask:0xf bound_ctrl:1
	v_add_f32_dpp v66, v66, v66 row_half_mirror row_mask:0xf bank_mask:0xf bound_ctrl:1
	s_nop 0
	v_add_f32_dpp v64, v64, v64 row_mirror row_mask:0xf bank_mask:0xf bound_ctrl:1
	v_add_f32_dpp v66, v66, v66 row_mirror row_mask:0xf bank_mask:0xf bound_ctrl:1
	s_nop 0
	v_cndmask_b32_dpp v72, v72, v64, vcc row_shr:1 row_mask:0xf bank_mask:0xf bound_ctrl:1
	v_cndmask_b32_dpp v73, v73, v66, vcc row_shr:1 row_mask:0xf bank_mask:0xf bound_ctrl:1
	v_sub_u32_e32 v79, 15, v101
	v_or_b32_e32 v79, 16, v79
	v_add_u32_e32 v77, 1, v79
	v_sub_u32_e32 v76, 32, v79
	v_cndmask_b32_e64 v76, v76, v77, s[36:37]
	v_add_u32_e32 v76, s28, v76
	v_ashrrev_i32_e32 v77, 31, v76
	v_lshl_add_u64 v[76:77], s[20:21], 0, v[76:77]
	v_lshlrev_b64 v[76:77], 9, v[76:77]
	v_cvt_pk_bf16_f32 v78, v72, v72
	v_lshl_add_u64 v[76:77], v[84:85], 0, v[76:77]
	global_store_short v[76:77], v78, off
	v_or_b32_e32 v76, s53, v79
	v_mov_b32_e32 v77, s54
	v_cvt_pk_bf16_f32 v79, v73, v73
	v_lshlrev_b64 v[76:77], 9, v[76:77]
	v_lshl_add_u64 v[76:77], v[86:87], 0, v[76:77]
	global_store_short v[76:77], v79, off
	s_branch .LBB0_1436
.Lrw_du_st0:
	v_sub_u32_e32 v79, 15, v101
	v_add_u32_e32 v77, 1, v79
	v_sub_u32_e32 v76, 32, v79
	v_cndmask_b32_e64 v76, v76, v77, s[36:37]
	v_add_u32_e32 v76, s28, v76
	v_ashrrev_i32_e32 v77, 31, v76
	v_lshl_add_u64 v[76:77], s[20:21], 0, v[76:77]
	v_lshlrev_b64 v[76:77], 9, v[76:77]
	v_cvt_pk_bf16_f32 v78, v72, v72
	v_lshl_add_u64 v[76:77], v[84:85], 0, v[76:77]
	global_store_short v[76:77], v78, off
	v_or_b32_e32 v76, s53, v79
	v_mov_b32_e32 v77, s54
	v_cvt_pk_bf16_f32 v79, v73, v73
	v_lshlrev_b64 v[76:77], 9, v[76:77]
	v_lshl_add_u64 v[76:77], v[86:87], 0, v[76:77]
	global_store_short v[76:77], v79, off
	s_branch .Lrw_du_back
.Lrw_nd_scan:
	v_mov_b32_e32 v72, v99
	v_mov_b32_e32 v73, v100
	v_cmp_eq_u32_e32 vcc, 0, v98
	ds_read_b128 v[220:223], v72 offset:25600
	ds_read_b128 v[216:219], v72 offset:25344
	ds_read_b128 v[228:231], v72 offset:26112
	ds_read_b32 v236, v73 offset:26624
	ds_read_b128 v[224:227], v72 offset:25856
	ds_read_b128 v[232:235], v72 offset:26368
	ds_read_b128 v[122:125], v72 offset:27136
	ds_read_b128 v[118:121], v72 offset:26880
	ds_read_b128 v[130:133], v72 offset:27648
	ds_read_b32 v138, v73 offset:28160
	ds_read_b128 v[126:129], v72 offset:27392
	ds_read_b128 v[134:137], v72 offset:27904
	s_mov_b32 s50, 0
.Lrw_nd_loop:
	s_waitcnt lgkmcnt(6)
	v_pk_mul_f32 v[64:65], v[60:61], v[220:221]
	v_pk_fma_f32 v[64:65], v[62:63], v[222:223], v[64:65]
	v_add_f32_e32 v66, v66, v67
	v_add_f32_e32 v64, v64, v65
	v_pk_mul_f32 v[60:61], v[60:61], v[216:217]
	v_pk_mul_f32 v[62:63], v[62:63], v[218:219]
	v_add_f32_dpp v64, v64, v64 quad_perm:[1,0,3,2] row_mask:0xf bank_mask:0xf bound_ctrl:1
	v_add_f32_dpp v66, v66, v66 quad_perm:[1,0,3,2] row_mask:0xf bank_mask:0xf bound_ctrl:1
	v_pk_fma_f32 v[60:61], v[236:237], v[228:229], v[60:61] op_sel_hi:[0,1,1]
	v_add_f32_dpp v64, v64, v64 quad_perm:[2,3,0,1] row_mask:0xf bank_mask:0xf bound_ctrl:1
	v_add_f32_dpp v66, v66, v66 quad_perm:[2,3,0,1] row_mask:0xf bank_mask:0xf bound_ctrl:1
	v_pk_fma_f32 v[62:63], v[236:237], v[230:231], v[62:63] op_sel_hi:[0,1,1]
	v_add_f32_dpp v64, v64, v64 row_half_mirror row_mask:0xf bank_mask:0xf bound_ctrl:1
	v_add_f32_dpp v66, v66, v66 row_half_mirror row_mask:0xf bank_mask:0xf bound_ctrl:1
	ds_read_b128 v[144:147], v72 offset:28672
	v_add_f32_dpp v64, v64, v64 row_mirror row_mask:0xf bank_mask:0xf bound_ctrl:1
	v_add_f32_dpp v66, v66, v66 row_mirror row_mask:0xf bank_mask:0xf bound_ctrl:1
	v_pk_fma_f32 v[60:61], v[224:225], v[64:65], v[60:61] op_sel_hi:[1,0,1] neg_lo:[1,0,0] neg_hi:[1,0,0]
	v_pk_fma_f32 v[62:63], v[226:227], v[64:65], v[62:63] op_sel_hi:[1,0,1] neg_lo:[1,0,0] neg_hi:[1,0,0]
	v_cndmask_b32_dpp v70, v70, v66, vcc row_shr:1 row_mask:0xf bank_mask:0xf bound_ctrl:1
	v_pk_mul_f32 v[66:67], v[232:233], v[60:61]
	v_pk_fma_f32 v[66:67], v[234:235], v[62:63], v[66:67]
	ds_read_b128 v[140:143], v72 offset:28416
	ds_read_b128 v[152:155], v72 offset:29184
	ds_read_b32 v160, v73 offset:29696
	ds_read_b128 v[148:151], v72 offset:28928
	ds_read_b128 v[156:159], v72 offset:29440
	s_waitcnt lgkmcnt(6)
	v_pk_mul_f32 v[64:65], v[60:61], v[122:123]
	v_pk_fma_f32 v[64:65], v[62:63], v[124:125], v[64:65]
	v_add_f32_e32 v66, v66, v67
	v_add_f32_e32 v64, v64, v65
	v_pk_mul_f32 v[60:61], v[60:61], v[118:119]
	v_pk_mul_f32 v[62:63], v[62:63], v[120:121]
	v_add_f32_dpp v64, v64, v64 quad_perm:[1,0,3,2] row_mask:0xf bank_mask:0xf bound_ctrl:1
	v_add_f32_dpp v66, v66, v66 quad_perm:[1,0,3,2] row_mask:0xf bank_mask:0xf bound_ctrl:1
	v_pk_fma_f32 v[60:61], v[138:139], v[130:131], v[60:61] op_sel_hi:[0,1,1]
	v_add_f32_dpp v64, v64, v64 quad_perm:[2,3,0,1] row_mask:0xf bank_mask:0xf bound_ctrl:1
	v_add_f32_dpp v66, v66, v66 quad_perm:[2,3,0,1] row_mask:0xf bank_mask:0xf bound_ctrl:1
	v_pk_fma_f32 v[62:63], v[138:139], v[132:133], v[62:63] op_sel_hi:[0,1,1]
	v_add_f32_dpp v64, v64, v64 row_half_mirror row_mask:0xf bank_mask:0xf bound_ctrl:1
	v_add_f32_dpp v66, v66, v66 row_half_mirror row_mask:0xf bank_mask:0xf bound_ctrl:1
	ds_read_b128 v[220:223], v72 offset:30208
	v_add_f32_dpp v64, v64, v64 row_mirror row_mask:0xf bank_mask:0xf bound_ctrl:1
	v_add_f32_dpp v66, v66, v66 row_mirror row_mask:0xf bank_mask:0xf bound_ctrl:1
	v_pk_fma_f32 v[60:61], v[126:127], v[64:65], v[60:61] op_sel_hi:[1,0,1] neg_lo:[1,0,0] neg_hi:[1,0,0]
	v_pk_fma_f32 v[62:63], v[128:129], v[64:65], v[62:63] op_sel_hi:[1,0,1] neg_lo:[1,0,0] neg_hi:[1,0,0]
	v_cndmask_b32_dpp v70, v70, v66, vcc row_shr:1 row_mask:0xf bank_mask:0xf bound_ctrl:1
	v_pk_mul_f32 v[66:67], v[134:135], v[60:61]
	v_pk_fma_f32 v[66:67], v[136:137], v[62:63], v[66:67]
	ds_read_b128 v[216:219], v72 offset:29952
	ds_read_b128 v[228:231], v72 offset:30720
	ds_read_b32 v236, v73 offset:31232
	ds_read_b128 v[224:227], v72 offset:30464
	ds_read_b128 v[232:235], v72 offset:30976
	s_waitcnt lgkmcnt(6)
; template <bool DUAL>
; __device__ __forceinline__ void rwkv_tile(const Params& p, int l, int tile, unsigned char* smem) {
;     ...
;       for (int i = 0; i < 32; ++i) {
;         const int inx = (i + 1) & 31;
;         const float4 nw4 = *(const float4*)(rp + inx * 384), nkk4 = *(const float4*)(rp + inx * 384 + 64), nkb4 = *(const float4*)(rp + inx * 384 + 128);
;         const float4 nkd4 = *(const float4*)(rp + inx * 384 + 192), nr4 = *(const float4*)(rp + inx * 384 + 256);
;         const float nv = vp[inx * 384];
;         v2f t = sA * (v2f){kk4.x, kk4.y};
;         t = sB * (v2f){kk4.z, kk4.w} + t;
;         float sa = t.x + t.y, ia = 0.f;
;         if (DUAL) {
;           v2f ti = iA * (v2f){kk4.x, kk4.y};
;           ti = iB * (v2f){kk4.z, kk4.w} + ti;
;           ia = ti.x + ti.y;
;           sa += dppf<0xB1>(sa); ia += dppf<0xB1>(ia);
;           sa += dppf<0x4E>(sa); ia += dppf<0x4E>(ia);
;           sa += dppf<0x141>(sa); ia += dppf<0x141>(ia);
;           sa += dppf<0x140>(sa); ia += dppf<0x140>(ia);
;         } else {
;           sa = sum16(sa);
;         }
;         v2f cA = sA * (v2f){w4.x, w4.y} + (v2f){kd4.x, kd4.y} * v;
;         v2f cB = sB * (v2f){w4.z, w4.w} + (v2f){kd4.z, kd4.w} * v;
;         sA = cA - (v2f){kb4.x, kb4.y} * sa;
;         sB = cB - (v2f){kb4.z, kb4.w} * sa;
;         v2f u = sA * (v2f){r4.x, r4.y};
;         u = sB * (v2f){r4.z, r4.w} + u;
;         float y = u.x + u.y, g = 0.f;
;         if (DUAL) {
;           iA = iA * (v2f){w4.x, w4.y} - (v2f){kb4.x, kb4.y} * ia;
;           iB = iB * (v2f){w4.z, w4.w} - (v2f){kb4.z, kb4.w} * ia;
;           v2f ui = iA * (v2f){r4.x, r4.y};
;           ui = iB * (v2f){r4.z, r4.w} + ui;
;           g = ui.x + ui.y;
;           y += dppf<0xB1>(y); g += dppf<0xB1>(g);
;           y += dppf<0x4E>(y); g += dppf<0x4E>(g);
;           y += dppf<0x141>(y); g += dppf<0x141>(g);
;           y += dppf<0x140>(y); g += dppf<0x140>(g);
;           if (fr == (i & 15)) gkeep = g;
;         } else {
;           y = sum16(y);
	v_pk_mul_f32 v[64:65], v[60:61], v[144:145]
	v_pk_fma_f32 v[64:65], v[62:63], v[146:147], v[64:65]
	v_add_f32_e32 v66, v66, v67
	v_add_f32_e32 v64, v64, v65
	v_pk_mul_f32 v[60:61], v[60:61], v[140:141]
	v_pk_mul_f32 v[62:63], v[62:63], v[142:143]
	v_add_f32_dpp v64, v64, v64 quad_perm:[1,0,3,2] row_mask:0xf bank_mask:0xf bound_ctrl:1
	v_add_f32_dpp v66, v66, v66 quad_perm:[1,0,3,2] row_mask:0xf bank_mask:0xf bound_ctrl:1
	v_pk_fma_f32 v[60:61], v[160:161], v[152:153], v[60:61] op_sel_hi:[0,1,1]
	v_add_f32_dpp v64, v64, v64 quad_perm:[2,3,0,1] row_mask:0xf bank_mask:0xf bound_ctrl:1
	v_add_f32_dpp v66, v66, v66 quad_perm:[2,3,0,1] row_mask:0xf bank_mask:0xf bound_ctrl:1
	v_pk_fma_f32 v[62:63], v[160:161], v[154:155], v[62:63] op_sel_hi:[0,1,1]
	v_add_f32_dpp v64, v64, v64 row_half_mirror row_mask:0xf bank_mask:0xf bound_ctrl:1
	v_add_f32_dpp v66, v66, v66 row_half_mirror row_mask:0xf bank_mask:0xf bound_ctrl:1
	ds_read_b128 v[122:125], v72 offset:31744
	v_add_f32_dpp v64, v64, v64 row_mirror row_mask:0xf bank_mask:0xf bound_ctrl:1
	v_add_f32_dpp v66, v66, v66 row_mirror row_mask:0xf bank_mask:0xf bound_ctrl:1
	v_pk_fma_f32 v[60:61], v[148:149], v[64:65], v[60:61] op_sel_hi:[1,0,1] neg_lo:[1,0,0] neg_hi:[1,0,0]
	v_pk_fma_f32 v[62:63], v[150:151], v[64:65], v[62:63] op_sel_hi:[1,0,1] neg_lo:[1,0,0] neg_hi:[1,0,0]
	v_cndmask_b32_dpp v70, v70, v66, vcc row_shr:1 row_mask:0xf bank_mask:0xf bound_ctrl:1
	v_pk_mul_f32 v[66:67], v[156:157], v[60:61]
	v_pk_fma_f32 v[66:67], v[158:159], v[62:63], v[66:67]
	ds_read_b128 v[118:121], v72 offset:31488
	ds_read_b128 v[130:133], v72 offset:32256
	ds_read_b32 v138, v73 offset:32768
	ds_read_b128 v[126:129], v72 offset:32000
	ds_read_b128 v[134:137], v72 offset:32512
	s_waitcnt lgkmcnt(6)
	v_pk_mul_f32 v[64:65], v[60:61], v[220:221]
	v_pk_fma_f32 v[64:65], v[62:63], v[222:223], v[64:65]
	v_add_f32_e32 v66, v66, v67
	v_add_f32_e32 v64, v64, v65
	v_pk_mul_f32 v[60:61], v[60:61], v[216:217]
	v_pk_mul_f32 v[62:63], v[62:63], v[218:219]
	v_add_f32_dpp v64, v64, v64 quad_perm:[1,0,3,2] row_mask:0xf bank_mask:0xf bound_ctrl:1
	v_add_f32_dpp v66, v66, v66 quad_perm:[1,0,3,2] row_mask:0xf bank_mask:0xf bound_ctrl:1
	v_pk_fma_f32 v[60:61], v[236:237], v[228:229], v[60:61] op_sel_hi:[0,1,1]
	v_add_f32_dpp v64, v64, v64 quad_perm:[2,3,0,1] row_mask:0xf bank_mask:0xf bound_ctrl:1
	v_add_f32_dpp v66, v66, v66 quad_perm:[2,3,0,1] row_mask:0xf bank_mask:0xf bound_ctrl:1
	v_pk_fma_f32 v[62:63], v[236:237], v[230:231], v[62:63] op_sel_hi:[0,1,1]
	v_add_f32_dpp v64, v64, v64 row_half_mirror row_mask:0xf bank_mask:0xf bound_ctrl:1
	v_add_f32_dpp v66, v66, v66 row_half_mirror row_mask:0xf bank_mask:0xf bound_ctrl:1
	ds_read_b128 v[144:147], v72 offset:33280
	v_add_f32_dpp v64, v64, v64 row_mirror row_mask:0xf bank_mask:0xf bound_ctrl:1
	v_add_f32_dpp v66, v66, v66 row_mirror row_mask:0xf bank_mask:0xf bound_ctrl:1
	v_pk_fma_f32 v[60:61], v[224:225], v[64:65], v[60:61] op_sel_hi:[1,0,1] neg_lo:[1,0,0] neg_hi:[1,0,0]
	v_pk_fma_f32 v[62:63], v[226:227], v[64:65], v[62:63] op_sel_hi:[1,0,1] neg_lo:[1,0,0] neg_hi:[1,0,0]
	v_cndmask_b32_dpp v70, v70, v66, vcc row_shr:1 row_mask:0xf bank_mask:0xf bound_ctrl:1
	v_pk_mul_f32 v[66:67], v[232:233], v[60:61]
	v_pk_fma_f32 v[66:67], v[234:235], v[62:63], v[66:67]
	ds_read_b128 v[140:143], v72 offset:33024
	ds_read_b128 v[152:155], v72 offset:33792
	ds_read_b32 v160, v73 offset:34304
	ds_read_b128 v[148:151], v72 offset:33536
	ds_read_b128 v[156:159], v72 offset:34048
	s_waitcnt lgkmcnt(6)
	v_pk_mul_f32 v[64:65], v[60:61], v[122:123]
	v_pk_fma_f32 v[64:65], v[62:63], v[124:125], v[64:65]
	v_add_f32_e32 v66, v66, v67
	v_add_f32_e32 v64, v64, v65
	v_pk_mul_f32 v[60:61], v[60:61], v[118:119]
	v_pk_mul_f32 v[62:63], v[62:63], v[120:121]
	v_add_f32_dpp v64, v64, v64 quad_perm:[1,0,3,2] row_mask:0xf bank_mask:0xf bound_ctrl:1
	v_add_f32_dpp v66, v66, v66 quad_perm:[1,0,3,2] row_mask:0xf bank_mask:0xf bound_ctrl:1
	v_pk_fma_f32 v[60:61], v[138:139], v[130:131], v[60:61] op_sel_hi:[0,1,1]
	v_add_f32_dpp v64, v64, v64 quad_perm:[2,3,0,1] row_mask:0xf bank_mask:0xf bound_ctrl:1
	v_add_f32_dpp v66, v66, v66 quad_perm:[2,3,0,1] row_mask:0xf bank_mask:0xf bound_ctrl:1
	v_pk_fma_f32 v[62:63], v[138:139], v[132:133], v[62:63] op_sel_hi:[0,1,1]
	v_add_f32_dpp v64, v64, v64 row_half_mirror row_mask:0xf bank_mask:0xf bound_ctrl:1
	v_add_f32_dpp v66, v66, v66 row_half_mirror row_mask:0xf bank_mask:0xf bound_ctrl:1
	ds_read_b128 v[220:223], v72 offset:34816
	v_add_f32_dpp v64, v64, v64 row_mirror row_mask:0xf bank_mask:0xf bound_ctrl:1
	v_add_f32_dpp v66, v66, v66 row_mirror row_mask:0xf bank_mask:0xf bound_ctrl:1
	v_pk_fma_f32 v[60:61], v[126:127], v[64:65], v[60:61] op_sel_hi:[1,0,1] neg_lo:[1,0,0] neg_hi:[1,0,0]
	v_pk_fma_f32 v[62:63], v[128:129], v[64:65], v[62:63] op_sel_hi:[1,0,1] neg_lo:[1,0,0] neg_hi:[1,0,0]
	v_cndmask_b32_dpp v70, v70, v66, vcc row_shr:1 row_mask:0xf bank_mask:0xf bound_ctrl:1
	s_cmp_eq_u32 s50, 2
	s_cbranch_scc1 .Lrw_nd_st0
; template <bool DUAL>
; __device__ __forceinline__ void rwkv_tile(const Params& p, int l, int tile, unsigned char* smem) {
;     ...
;       for (int i = 0; i < 32; ++i) {
;         const int inx = (i + 1) & 31;
;         const float4 nw4 = *(const float4*)(rp + inx * 384), nkk4 = *(const float4*)(rp + inx * 384 + 64), nkb4 = *(const float4*)(rp + inx * 384 + 128);
;         const float4 nkd4 = *(const float4*)(rp + inx * 384 + 192), nr4 = *(const float4*)(rp + inx * 384 + 256);
;         const float nv = vp[inx * 384];
;         v2f t = sA * (v2f){kk4.x, kk4.y};
;         t = sB * (v2f){kk4.z, kk4.w} + t;
;         float sa = t.x + t.y, ia = 0.f;
;         if (DUAL) {
;           v2f ti = iA * (v2f){kk4.x, kk4.y};
;           ti = iB * (v2f){kk4.z, kk4.w} + ti;
;           ia = ti.x + ti.y;
;           sa += dppf<0xB1>(sa); ia += dppf<0xB1>(ia);
;           sa += dppf<0x4E>(sa); ia += dppf<0x4E>(ia);
;           sa += dppf<0x141>(sa); ia += dppf<0x141>(ia);
;           sa += dppf<0x140>(sa); ia += dppf<0x140>(ia);
;         } else {
;           sa = sum16(sa);
;         }
;         v2f cA = sA * (v2f){w4.x, w4.y} + (v2f){kd4.x, kd4.y} * v;
;         v2f cB = sB * (v2f){w4.z, w4.w} + (v2f){kd4.z, kd4.w} * v;
;         sA = cA - (v2f){kb4.x, kb4.y} * sa;
;         sB = cB - (v2f){kb4.z, kb4.w} * sa;
;         v2f u = sA * (v2f){r4.x, r4.y};
;         u = sB * (v2f){r4.z, r4.w} + u;
;         float y = u.x + u.y, g = 0.f;
;         if (DUAL) {
;           iA = iA * (v2f){w4.x, w4.y} - (v2f){kb4.x, kb4.y} * ia;
;           iB = iB * (v2f){w4.z, w4.w} - (v2f){kb4.z, kb4.w} * ia;
;           v2f ui = iA * (v2f){r4.x, r4.y};
;           ui = iB * (v2f){r4.z, r4.w} + ui;
;           g = ui.x + ui.y;
;           y += dppf<0xB1>(y); g += dppf<0xB1>(g);
;           y += dppf<0x4E>(y); g += dppf<0x4E>(g);
;           y += dppf<0x141>(y); g += dppf<0x141>(g);
;           y += dppf<0x140>(y); g += dppf<0x140>(g);
;           if (fr == (i & 15)) gkeep = g;
;         } else {
;           y = sum16(y);
;         }
;         if (fr == (i & 15)) ykeep = y;
;         if ((i & 15) == 15) {
;           const int ii = (i & 16) + fr;
;           const int ri = (d == 0) ? ii + 1 : 32 - ii;
;           const int pi = plo - 1 + ri;
;           p.yR[((size_t)d * TOK + rowbase + pi) * 256 + h * 64 + row] = f2bf(ykeep);
.Lrw_nd_back:
	v_pk_mul_f32 v[66:67], v[134:135], v[60:61]
	v_pk_fma_f32 v[66:67], v[136:137], v[62:63], v[66:67]
	ds_read_b128 v[216:219], v72 offset:34560
	ds_read_b128 v[228:231], v72 offset:35328
	ds_read_b32 v236, v73 offset:35840
	ds_read_b128 v[224:227], v72 offset:35072
	ds_read_b128 v[232:235], v72 offset:35584
	s_waitcnt lgkmcnt(6)
	v_pk_mul_f32 v[64:65], v[60:61], v[144:145]
	v_pk_fma_f32 v[64:65], v[62:63], v[146:147], v[64:65]
	v_add_f32_e32 v66, v66, v67
	v_add_f32_e32 v64, v64, v65
	v_pk_mul_f32 v[60:61], v[60:61], v[140:141]
	v_pk_mul_f32 v[62:63], v[62:63], v[142:143]
	v_add_f32_dpp v64, v64, v64 quad_perm:[1,0,3,2] row_mask:0xf bank_mask:0xf bound_ctrl:1
	v_add_f32_dpp v66, v66, v66 quad_perm:[1,0,3,2] row_mask:0xf bank_mask:0xf bound_ctrl:1
	v_pk_fma_f32 v[60:61], v[160:161], v[152:153], v[60:61] op_sel_hi:[0,1,1]
	v_add_f32_dpp v64, v64, v64 quad_perm:[2,3,0,1] row_mask:0xf bank_mask:0xf bound_ctrl:1
	v_add_f32_dpp v66, v66, v66 quad_perm:[2,3,0,1] row_mask:0xf bank_mask:0xf bound_ctrl:1
	v_pk_fma_f32 v[62:63], v[160:161], v[154:155], v[62:63] op_sel_hi:[0,1,1]
	v_add_f32_dpp v64, v64, v64 row_half_mirror row_mask:0xf bank_mask:0xf bound_ctrl:1
	v_add_f32_dpp v66, v66, v66 row_half_mirror row_mask:0xf bank_mask:0xf bound_ctrl:1
	ds_read_b128 v[122:125], v72 offset:36352
	v_add_f32_dpp v64, v64, v64 row_mirror row_mask:0xf bank_mask:0xf bound_ctrl:1
	v_add_f32_dpp v66, v66, v66 row_mirror row_mask:0xf bank_mask:0xf bound_ctrl:1
	v_pk_fma_f32 v[60:61], v[148:149], v[64:65], v[60:61] op_sel_hi:[1,0,1] neg_lo:[1,0,0] neg_hi:[1,0,0]
	v_pk_fma_f32 v[62:63], v[150:151], v[64:65], v[62:63] op_sel_hi:[1,0,1] neg_lo:[1,0,0] neg_hi:[1,0,0]
	v_cndmask_b32_dpp v70, v70, v66, vcc row_shr:1 row_mask:0xf bank_mask:0xf bound_ctrl:1
	v_pk_mul_f32 v[66:67], v[156:157], v[60:61]
	v_pk_fma_f32 v[66:67], v[158:159], v[62:63], v[66:67]
	ds_read_b128 v[118:121], v72 offset:36096
	ds_read_b128 v[130:133], v72 offset:36864
	ds_read_b32 v138, v73 offset:37376
	ds_read_b128 v[126:129], v72 offset:36608
	ds_read_b128 v[134:137], v72 offset:37120
	v_add_u32_e32 v72, 0x2400, v72
	v_add_u32_e32 v73, 0x2400, v73
	s_add_i32 s50, s50, 1
	s_cmp_lg_u32 s50, 5
	s_cbranch_scc1 .Lrw_nd_loop
	s_waitcnt lgkmcnt(6)
	v_pk_mul_f32 v[64:65], v[60:61], v[220:221]
	v_pk_fma_f32 v[64:65], v[62:63], v[222:223], v[64:65]
	v_add_f32_e32 v66, v66, v67
	v_add_f32_e32 v64, v64, v65
	v_pk_mul_f32 v[60:61], v[60:61], v[216:217]
	v_pk_mul_f32 v[62:63], v[62:63], v[218:219]
	v_add_f32_dpp v64, v64, v64 quad_perm:[1,0,3,2] row_mask:0xf bank_mask:0xf bound_ctrl:1
	v_add_f32_dpp v66, v66, v66 quad_perm:[1,0,3,2] row_mask:0xf bank_mask:0xf bound_ctrl:1
	v_pk_fma_f32 v[60:61], v[236:237], v[228:229], v[60:61] op_sel_hi:[0,1,1]
	v_add_f32_dpp v64, v64, v64 quad_perm:[2,3,0,1] row_mask:0xf bank_mask:0xf bound_ctrl:1
	v_add_f32_dpp v66, v66, v66 quad_perm:[2,3,0,1] row_mask:0xf bank_mask:0xf bound_ctrl:1
	v_pk_fma_f32 v[62:63], v[236:237], v[230:231], v[62:63] op_sel_hi:[0,1,1]
	v_add_f32_dpp v64, v64, v64 row_half_mirror row_mask:0xf bank_mask:0xf bound_ctrl:1
	v_add_f32_dpp v66, v66, v66 row_half_mirror row_mask:0xf bank_mask:0xf bound_ctrl:1
	s_nop 0
	v_add_f32_dpp v64, v64, v64 row_mirror row_mask:0xf bank_mask:0xf bound_ctrl:1
	v_add_f32_dpp v66, v66, v66 row_mirror row_mask:0xf bank_mask:0xf bound_ctrl:1
	v_pk_fma_f32 v[60:61], v[224:225], v[64:65], v[60:61] op_sel_hi:[1,0,1] neg_lo:[1,0,0] neg_hi:[1,0,0]
	v_pk_fma_f32 v[62:63], v[226:227], v[64:65], v[62:63] op_sel_hi:[1,0,1] neg_lo:[1,0,0] neg_hi:[1,0,0]
	v_cndmask_b32_dpp v70, v70, v66, vcc row_shr:1 row_mask:0xf bank_mask:0xf bound_ctrl:1
	v_pk_mul_f32 v[66:67], v[232:233], v[60:61]
	v_pk_fma_f32 v[66:67], v[234:235], v[62:63], v[66:67]
	s_waitcnt lgkmcnt(0)
	v_pk_mul_f32 v[64:65], v[60:61], v[122:123]
	v_pk_fma_f32 v[64:65], v[62:63], v[124:125], v[64:65]
	v_add_f32_e32 v66, v66, v67
	v_add_f32_e32 v64, v64, v65
	v_pk_mul_f32 v[60:61], v[60:61], v[118:119]
	v_pk_mul_f32 v[62:63], v[62:63], v[120:121]
	v_add_f32_dpp v64, v64, v64 quad_perm:[1,0,3,2] row_mask:0xf bank_mask:0xf bound_ctrl:1
	v_add_f32_dpp v66, v66, v66 quad_perm:[1,0,3,2] row_mask:0xf bank_mask:0xf bound_ctrl:1
	v_pk_fma_f32 v[60:61], v[138:139], v[130:131], v[60:61] op_sel_hi:[0,1,1]
	v_add_f32_dpp v64, v64, v64 quad_perm:[2,3,0,1] row_mask:0xf bank_mask:0xf bound_ctrl:1
	v_add_f32_dpp v66, v66, v66 quad_perm:[2,3,0,1] row_mask:0xf bank_mask:0xf bound_ctrl:1
	v_pk_fma_f32 v[62:63], v[138:139], v[132:133], v[62:63] op_sel_hi:[0,1,1]
	v_add_f32_dpp v64, v64, v64 row_half_mirror row_mask:0xf bank_mask:0xf bound_ctrl:1
	v_add_f32_dpp v66, v66, v66 row_half_mirror row_mask:0xf bank_mask:0xf bound_ctrl:1
	s_nop 0
	v_add_f32_dpp v64, v64, v64 row_mirror row_mask:0xf bank_mask:0xf bound_ctrl:1
	v_add_f32_dpp v66, v66, v66 row_mirror row_mask:0xf bank_mask:0xf bound_ctrl:1
	v_pk_fma_f32 v[60:61], v[126:127], v[64:65], v[60:61] op_sel_hi:[1,0,1] neg_lo:[1,0,0] neg_hi:[1,0,0]
	v_pk_fma_f32 v[62:63], v[128:129], v[64:65], v[62:63] op_sel_hi:[1,0,1] neg_lo:[1,0,0] neg_hi:[1,0,0]
	v_cndmask_b32_dpp v70, v70, v66, vcc row_shr:1 row_mask:0xf bank_mask:0xf bound_ctrl:1
	v_pk_mul_f32 v[66:67], v[134:135], v[60:61]
	v_pk_fma_f32 v[66:67], v[136:137], v[62:63], v[66:67]
	v_add_f32_e32 v66, v66, v67
	s_nop 1
	s_nop 1
	v_add_f32_dpp v66, v66, v66 quad_perm:[1,0,3,2] row_mask:0xf bank_mask:0xf bound_ctrl:1
	s_nop 1
	v_add_f32_dpp v66, v66, v66 quad_perm:[2,3,0,1] row_mask:0xf bank_mask:0xf bound_ctrl:1
	s_nop 1
	v_add_f32_dpp v66, v66, v66 row_half_mirror row_mask:0xf bank_mask:0xf bound_ctrl:1
	s_nop 1
	v_add_f32_dpp v66, v66, v66 row_mirror row_mask:0xf bank_mask:0xf bound_ctrl:1
	v_cndmask_b32_dpp v70, v70, v66, vcc row_shr:1 row_mask:0xf bank_mask:0xf bound_ctrl:1
	v_sub_u32_e32 v77, 15, v98
	v_or_b32_e32 v77, 16, v77
	v_add_u32_e32 v75, 1, v77
	v_sub_u32_e32 v74, 32, v77
	v_cndmask_b32_e64 v74, v74, v75, s[36:37]
	v_add_u32_e32 v74, s28, v74
	v_ashrrev_i32_e32 v75, 31, v74
	v_lshl_add_u64 v[74:75], s[20:21], 0, v[74:75]
	v_lshlrev_b64 v[74:75], 9, v[74:75]
	v_cvt_pk_bf16_f32 v76, v70, v70
	v_lshl_add_u64 v[74:75], v[90:91], 0, v[74:75]
	global_store_short v[74:75], v76, off
	s_branch .LBB0_1491
.Lrw_nd_st0:
	v_sub_u32_e32 v77, 15, v98
	v_add_u32_e32 v75, 1, v77
	v_sub_u32_e32 v74, 32, v77
	v_cndmask_b32_e64 v74, v74, v75, s[36:37]
	v_add_u32_e32 v74, s28, v74
	v_ashrrev_i32_e32 v75, 31, v74
	v_lshl_add_u64 v[74:75], s[20:21], 0, v[74:75]
	v_lshlrev_b64 v[74:75], 9, v[74:75]
	v_cvt_pk_bf16_f32 v76, v70, v70
	v_lshl_add_u64 v[74:75], v[90:91], 0, v[74:75]
	global_store_short v[74:75], v76, off
	s_branch .Lrw_nd_back
